# p0a: even workgroups additionally run the Ktab section before the x->bf16 streaming section
# baseline (speedup 1.0000x reference)
.LBB7_217:
	s_or_b64 exec, exec, s[24:25]
	s_cmp_eq_u32 s100, 3
	s_cbranch_scc1 .Lp0_K
	s_cmp_eq_u32 s100, 0
	s_cbranch_scc0 .Lp0_X
	s_mov_b32 s100, 4
	s_waitcnt vmcnt(0)
	s_branch .Lp0_K
.Lp0_X:
	s_cmp_lt_i32 s70, 0x9000
	s_cbranch_scc0 .LBB7_239
	v_lshlrev_b32_e32 v32, 2, v201
	v_mov_b32_e32 v33, 0
	v_lshl_add_u64 v[0:1], s[22:23], 0, v[32:33]
	s_mov_b64 s[8:9], 0x1ce80000
	v_lshl_add_u64 v[34:35], v[0:1], 0, s[8:9]
	v_mbcnt_lo_u32_b32 v0, -1, 0
	v_mbcnt_hi_u32_b32 v37, -1, v0
	s_add_u32 s16, s22, 0x1cd80000
	v_and_b32_e32 v0, 64, v37
	v_cmp_eq_u32_e64 s[6:7], 0, v201
	s_addc_u32 s17, s23, 0
	v_lshlrev_b32_e32 v36, 4, v201
	s_mov_b32 s18, 0xa380000
	v_lshlrev_b32_e32 v32, 1, v32
	s_waitcnt vmcnt(7)
	v_add_u32_e32 v38, 64, v0
	s_waitcnt vmcnt(6)
	v_xor_b32_e32 v39, 1, v37
	s_waitcnt vmcnt(5)
	v_xor_b32_e32 v40, 2, v37
	s_waitcnt vmcnt(4)
	v_mov_b32_e32 v41, 0x358637bd
	s_mov_b32 s19, 0x800000
	v_xor_b32_e32 v42, 4, v37
	v_xor_b32_e32 v43, 8, v37
	s_mov_b32 s10, s70
	s_branch .LBB7_221

.LBB7_239:
	s_cmp_eq_u32 s100, 5
	s_cbranch_scc1 .Lp0_fin
	s_cmp_eq_u32 s100, 2
	s_cbranch_scc0 .Lp0_K
	s_mov_b32 s100, 3
	s_waitcnt vmcnt(0)
	s_branch .Lp0_P

.LBB7_258:
	s_cmp_eq_u32 s100, 4
	s_cbranch_scc0 .Lp0_fin
	s_mov_b32 s100, 5
	s_load_dwordx2 s[22:23], s[20:21], 0x120
	s_waitcnt vmcnt(0) lgkmcnt(0)
	s_mov_b64 s[24:25], exec
	s_branch .LBB7_217
